# phase-start operand warm-up: at the seams before the up- and down-projection every thread touches the first two K-slices of its first tile's A and B panels into L2 while the workgroup waits
# speedup vs baseline: 1.0005x; 1.0005x over previous
; __device__ __forceinline__ unsigned cvt_pk_bf16(float lo, float hi) { unsigned r; asm volatile("v_cvt_pk_bf16_f32 %0, %1, %2" : "=v"(r) : "v"(lo), "v"(hi)); return r; }
; __global__ void __launch_bounds__(512, 2) trunk_fwd(Args args) {
;     ...
;             const float* pl = KIN(1) + (size_t)L * M * PLE;
;     ...
;                     u32x2 pw; pw.x = cvt_pk_bf16(pv4[0], pv4[1]); pw.y = cvt_pk_bf16(pv4[2], pv4[3]);
;                     *(u32x2*)(PB + (size_t)r * PLE + lane * 4) = pw;
.LBB0_507:
	v_readlane_b32 s4, v254, 63
	s_nop 1
	v_writelane_b32 v255, s4, 41
	v_readlane_b32 s4, v254, 2
	s_nop 3
	v_mov_b32_e32 v0, s4
	ds_read_b32 v0, v0
	s_waitcnt lgkmcnt(0)
	v_readfirstlane_b32 s4, v0
	v_readfirstlane_b32 s5, v163
	s_nop 3
	s_cmp_lt_u32 s4, 0x80
	s_cbranch_scc1 .Lpc_skip
	s_load_dwordx2 s[6:7], s[94:95], 0x8
	s_load_dwordx2 s[18:19], s[94:95], 0xc0
	s_lshr_b32 s5, s5, 6
	s_and_b32 s40, s4, 7
	s_lshr_b32 s4, s4, 3
	s_sub_u32 s4, s4, 16
	s_lshl_b32 s4, s4, 3
	s_add_u32 s4, s4, s5
	s_lshl_b32 s4, s4, 5
	s_lshl_b32 s40, s40, 12
	s_add_u32 s40, s40, s4
	s_mov_b32 s41, 0
	v_readlane_b32 s38, v254, 63
	s_mov_b32 s39, 0
	v_and_b32_e32 v2, 63, v163
	v_lshlrev_b32_e32 v3, 3, v2
	v_lshlrev_b32_e32 v2, 4, v2
	s_lshl_b64 s[38:39], s[38:39], 25
	s_lshl_b64 s[4:5], s[40:41], 10
	s_lshl_b64 s[40:41], s[40:41], 9
	s_waitcnt lgkmcnt(0)
	s_add_u32 s6, s6, s38
	s_addc_u32 s7, s7, s39
	s_add_u32 s6, s6, s4
	s_addc_u32 s7, s7, s5
	s_add_u32 s18, s18, 0x1d500000
	s_addc_u32 s19, s19, 0
	s_add_u32 s18, s18, s40
	s_addc_u32 s19, s19, s41
	global_load_dwordx4 v[4:7], v2, s[6:7]
	global_load_dwordx4 v[8:11], v2, s[6:7] offset:1024
	global_load_dwordx4 v[12:15], v2, s[6:7] offset:2048
	global_load_dwordx4 v[16:19], v2, s[6:7] offset:3072
	s_add_u32 s6, s6, 0x1000
	s_addc_u32 s7, s7, 0
	global_load_dwordx4 v[20:23], v2, s[6:7]
	global_load_dwordx4 v[24:27], v2, s[6:7] offset:1024
	global_load_dwordx4 v[28:31], v2, s[6:7] offset:2048
	global_load_dwordx4 v[32:35], v2, s[6:7] offset:3072
	s_add_u32 s6, s6, 0x1000
	s_addc_u32 s7, s7, 0
	s_waitcnt vmcnt(7)
	v_cvt_pk_bf16_f32 v4, v4, v5
	v_cvt_pk_bf16_f32 v5, v6, v7
	s_waitcnt vmcnt(6)
	v_cvt_pk_bf16_f32 v8, v8, v9
	v_cvt_pk_bf16_f32 v9, v10, v11
	s_waitcnt vmcnt(5)
	v_cvt_pk_bf16_f32 v12, v12, v13
	v_cvt_pk_bf16_f32 v13, v14, v15
	s_waitcnt vmcnt(4)
	v_cvt_pk_bf16_f32 v16, v16, v17
	v_cvt_pk_bf16_f32 v17, v18, v19
	s_waitcnt vmcnt(3)
	v_cvt_pk_bf16_f32 v20, v20, v21
	v_cvt_pk_bf16_f32 v21, v22, v23
	s_waitcnt vmcnt(2)
	v_cvt_pk_bf16_f32 v24, v24, v25
	v_cvt_pk_bf16_f32 v25, v26, v27
	s_waitcnt vmcnt(1)
	v_cvt_pk_bf16_f32 v28, v28, v29
	v_cvt_pk_bf16_f32 v29, v30, v31
	s_waitcnt vmcnt(0)
	v_cvt_pk_bf16_f32 v32, v32, v33
	v_cvt_pk_bf16_f32 v33, v34, v35
	global_store_dwordx2 v3, v[4:5], s[18:19]
	global_store_dwordx2 v3, v[8:9], s[18:19] offset:512
	global_store_dwordx2 v3, v[12:13], s[18:19] offset:1024
	global_store_dwordx2 v3, v[16:17], s[18:19] offset:1536
	global_store_dwordx2 v3, v[20:21], s[18:19] offset:2048
	global_store_dwordx2 v3, v[24:25], s[18:19] offset:2560
	global_store_dwordx2 v3, v[28:29], s[18:19] offset:3072
	global_store_dwordx2 v3, v[32:33], s[18:19] offset:3584
	s_add_u32 s18, s18, 0x1000
	s_addc_u32 s19, s19, 0
	global_load_dwordx4 v[4:7], v2, s[6:7]
	global_load_dwordx4 v[8:11], v2, s[6:7] offset:1024
	global_load_dwordx4 v[12:15], v2, s[6:7] offset:2048
	global_load_dwordx4 v[16:19], v2, s[6:7] offset:3072
	s_add_u32 s6, s6, 0x1000
	s_addc_u32 s7, s7, 0
	global_load_dwordx4 v[20:23], v2, s[6:7]
	global_load_dwordx4 v[24:27], v2, s[6:7] offset:1024
	global_load_dwordx4 v[28:31], v2, s[6:7] offset:2048
	global_load_dwordx4 v[32:35], v2, s[6:7] offset:3072
	s_add_u32 s6, s6, 0x1000
	s_addc_u32 s7, s7, 0
	s_waitcnt vmcnt(7)
	v_cvt_pk_bf16_f32 v4, v4, v5
	v_cvt_pk_bf16_f32 v5, v6, v7
	s_waitcnt vmcnt(6)
	v_cvt_pk_bf16_f32 v8, v8, v9
	v_cvt_pk_bf16_f32 v9, v10, v11
	s_waitcnt vmcnt(5)
	v_cvt_pk_bf16_f32 v12, v12, v13
	v_cvt_pk_bf16_f32 v13, v14, v15
	s_waitcnt vmcnt(4)
	v_cvt_pk_bf16_f32 v16, v16, v17
	v_cvt_pk_bf16_f32 v17, v18, v19
	s_waitcnt vmcnt(3)
	v_cvt_pk_bf16_f32 v20, v20, v21
	v_cvt_pk_bf16_f32 v21, v22, v23
	s_waitcnt vmcnt(2)
	v_cvt_pk_bf16_f32 v24, v24, v25
	v_cvt_pk_bf16_f32 v25, v26, v27
	s_waitcnt vmcnt(1)
	v_cvt_pk_bf16_f32 v28, v28, v29
	v_cvt_pk_bf16_f32 v29, v30, v31
	s_waitcnt vmcnt(0)
; __device__ __forceinline__ unsigned cvt_pk_bf16(float lo, float hi) { unsigned r; asm volatile("v_cvt_pk_bf16_f32 %0, %1, %2" : "=v"(r) : "v"(lo), "v"(hi)); return r; }
; __global__ void __launch_bounds__(512, 2) trunk_fwd(Args args) {
;     ...
;             const float* pl = KIN(1) + (size_t)L * M * PLE;
;     ...
;                     u32x2 pw; pw.x = cvt_pk_bf16(pv4[0], pv4[1]); pw.y = cvt_pk_bf16(pv4[2], pv4[3]);
;                     *(u32x2*)(PB + (size_t)r * PLE + lane * 4) = pw;
	v_cvt_pk_bf16_f32 v32, v32, v33
	v_cvt_pk_bf16_f32 v33, v34, v35
	global_store_dwordx2 v3, v[4:5], s[18:19]
	global_store_dwordx2 v3, v[8:9], s[18:19] offset:512
	global_store_dwordx2 v3, v[12:13], s[18:19] offset:1024
	global_store_dwordx2 v3, v[16:17], s[18:19] offset:1536
	global_store_dwordx2 v3, v[20:21], s[18:19] offset:2048
	global_store_dwordx2 v3, v[24:25], s[18:19] offset:2560
	global_store_dwordx2 v3, v[28:29], s[18:19] offset:3072
	global_store_dwordx2 v3, v[32:33], s[18:19] offset:3584
	s_add_u32 s18, s18, 0x1000
	s_addc_u32 s19, s19, 0
	global_load_dwordx4 v[4:7], v2, s[6:7]
	global_load_dwordx4 v[8:11], v2, s[6:7] offset:1024
	global_load_dwordx4 v[12:15], v2, s[6:7] offset:2048
	global_load_dwordx4 v[16:19], v2, s[6:7] offset:3072
	s_add_u32 s6, s6, 0x1000
	s_addc_u32 s7, s7, 0
	global_load_dwordx4 v[20:23], v2, s[6:7]
	global_load_dwordx4 v[24:27], v2, s[6:7] offset:1024
	global_load_dwordx4 v[28:31], v2, s[6:7] offset:2048
	global_load_dwordx4 v[32:35], v2, s[6:7] offset:3072
	s_add_u32 s6, s6, 0x1000
	s_addc_u32 s7, s7, 0
	s_waitcnt vmcnt(7)
	v_cvt_pk_bf16_f32 v4, v4, v5
	v_cvt_pk_bf16_f32 v5, v6, v7
	s_waitcnt vmcnt(6)
	v_cvt_pk_bf16_f32 v8, v8, v9
	v_cvt_pk_bf16_f32 v9, v10, v11
	s_waitcnt vmcnt(5)
	v_cvt_pk_bf16_f32 v12, v12, v13
	v_cvt_pk_bf16_f32 v13, v14, v15
	s_waitcnt vmcnt(4)
	v_cvt_pk_bf16_f32 v16, v16, v17
	v_cvt_pk_bf16_f32 v17, v18, v19
	s_waitcnt vmcnt(3)
	v_cvt_pk_bf16_f32 v20, v20, v21
	v_cvt_pk_bf16_f32 v21, v22, v23
	s_waitcnt vmcnt(2)
	v_cvt_pk_bf16_f32 v24, v24, v25
	v_cvt_pk_bf16_f32 v25, v26, v27
	s_waitcnt vmcnt(1)
	v_cvt_pk_bf16_f32 v28, v28, v29
	v_cvt_pk_bf16_f32 v29, v30, v31
	s_waitcnt vmcnt(0)
	v_cvt_pk_bf16_f32 v32, v32, v33
	v_cvt_pk_bf16_f32 v33, v34, v35
	global_store_dwordx2 v3, v[4:5], s[18:19]
	global_store_dwordx2 v3, v[8:9], s[18:19] offset:512
	global_store_dwordx2 v3, v[12:13], s[18:19] offset:1024
	global_store_dwordx2 v3, v[16:17], s[18:19] offset:1536
	global_store_dwordx2 v3, v[20:21], s[18:19] offset:2048
	global_store_dwordx2 v3, v[24:25], s[18:19] offset:2560
	global_store_dwordx2 v3, v[28:29], s[18:19] offset:3072
	global_store_dwordx2 v3, v[32:33], s[18:19] offset:3584
	s_add_u32 s18, s18, 0x1000
	s_addc_u32 s19, s19, 0
	global_load_dwordx4 v[4:7], v2, s[6:7]
	global_load_dwordx4 v[8:11], v2, s[6:7] offset:1024
	global_load_dwordx4 v[12:15], v2, s[6:7] offset:2048
	global_load_dwordx4 v[16:19], v2, s[6:7] offset:3072
	s_add_u32 s6, s6, 0x1000
	s_addc_u32 s7, s7, 0
	global_load_dwordx4 v[20:23], v2, s[6:7]
	global_load_dwordx4 v[24:27], v2, s[6:7] offset:1024
	global_load_dwordx4 v[28:31], v2, s[6:7] offset:2048
	global_load_dwordx4 v[32:35], v2, s[6:7] offset:3072
	s_add_u32 s6, s6, 0x1000
	s_addc_u32 s7, s7, 0
	s_waitcnt vmcnt(7)
	v_cvt_pk_bf16_f32 v4, v4, v5
	v_cvt_pk_bf16_f32 v5, v6, v7
	s_waitcnt vmcnt(6)
	v_cvt_pk_bf16_f32 v8, v8, v9
	v_cvt_pk_bf16_f32 v9, v10, v11
	s_waitcnt vmcnt(5)
	v_cvt_pk_bf16_f32 v12, v12, v13
	v_cvt_pk_bf16_f32 v13, v14, v15
	s_waitcnt vmcnt(4)
	v_cvt_pk_bf16_f32 v16, v16, v17
	v_cvt_pk_bf16_f32 v17, v18, v19
	s_waitcnt vmcnt(3)
	v_cvt_pk_bf16_f32 v20, v20, v21
	v_cvt_pk_bf16_f32 v21, v22, v23
	s_waitcnt vmcnt(2)
	v_cvt_pk_bf16_f32 v24, v24, v25
	v_cvt_pk_bf16_f32 v25, v26, v27
	s_waitcnt vmcnt(1)
	v_cvt_pk_bf16_f32 v28, v28, v29
	v_cvt_pk_bf16_f32 v29, v30, v31
	s_waitcnt vmcnt(0)
	v_cvt_pk_bf16_f32 v32, v32, v33
	v_cvt_pk_bf16_f32 v33, v34, v35
	global_store_dwordx2 v3, v[4:5], s[18:19]
	global_store_dwordx2 v3, v[8:9], s[18:19] offset:512
	global_store_dwordx2 v3, v[12:13], s[18:19] offset:1024
	global_store_dwordx2 v3, v[16:17], s[18:19] offset:1536
	global_store_dwordx2 v3, v[20:21], s[18:19] offset:2048
	global_store_dwordx2 v3, v[24:25], s[18:19] offset:2560
	global_store_dwordx2 v3, v[28:29], s[18:19] offset:3072
	global_store_dwordx2 v3, v[32:33], s[18:19] offset:3584
	s_add_u32 s18, s18, 0x1000
	s_addc_u32 s19, s19, 0

; #define PG8_STAGE(bufoff, gbase, voff) do { _Pragma("unroll") for (int _i = 0; _i < 2; ++_i) \
;         __builtin_amdgcn_global_load_lds((const unsigned*)((const char*)(gbase) + (voff)[_i]), (LAS unsigned*)(lds + (bufoff) + ldsw + _i * 8192), 16, 0, 0); } while (0)
; __device__ __forceinline__ unsigned xb_ld(unsigned* p)              { return __hip_atomic_load(p, __ATOMIC_RELAXED, __HIP_MEMORY_SCOPE_AGENT); }
; __device__ __forceinline__ unsigned xb_add(unsigned* p, unsigned v) { return __hip_atomic_fetch_add(p, v, __ATOMIC_RELAXED, __HIP_MEMORY_SCOPE_AGENT); }
; #define XB_SPIN(cond, bar) do { unsigned _sp = 0; while (cond) { __builtin_amdgcn_s_sleep(1); \
;     if ((++_sp & 255u) == 0u) { if (xb_ld(&(bar)[XB_TMO])) break; if (_sp > XB_SPIN_CAP) { atomicAdd(&(bar)[XB_TMO], 1u); break; } } } } while (0)
; template <class Epi, bool MID = false>
; __device__ __forceinline__ void gemm_phase(LAS unsigned char* lds, const Gemm g, const StaticOrder& S, const Epi& E) {
;     ...
;     const char* cA = (const char*)g.A + (size_t)cur.pm * tstepA; const char* cB = (const char*)g.Bt + (size_t)cur.pn * tstepB;
;     PG8_STAGE(PG8_SB(0, 0), cB, voffB); PG8_STAGE(PG8_SB(0, 1), cB + hstepB, voffB); PG8_STAGE(PG8_SA(0, 0), cA, voffA); PG8_STAGE(PG8_SA(0, 1), cA + hstepA, voffA);
; __device__ __forceinline__ void xcd_local_barrier(const XcdBarrier& b, unsigned nloc) {
;     asm volatile("s_waitcnt vmcnt(0)" ::: "memory");
;     __syncthreads();
;     if (threadIdx.x == 0) {
;         unsigned* bar = b.bar;
;         __builtin_amdgcn_s_waitcnt(0);
;         const unsigned old = xb_add(&bar[XB_LSUB(b.x)], 1u);
;         const unsigned gen = old / nloc;
;         if (old + 1u == (gen + 1u) * nloc) xb_add(&bar[XB_LGEN(b.x)], 1u);
;         else XB_SPIN(xb_ld(&bar[XB_LGEN(b.x)]) == gen, bar);
;         __builtin_amdgcn_fence(__ATOMIC_ACQUIRE, "agent");
;         asm volatile("s_waitcnt vmcnt(0)" ::: "memory");
;     }
.LBB0_1367:
	v_readlane_b32 s0, v254, 60
	v_mov_b32 v0, s0
	ds_read_b32 v0, v0
	s_waitcnt lgkmcnt(0)
	s_nop 0
	v_readfirstlane_b32 s0, v0
	s_cmp_eq_u32 s0, 0
	s_cbranch_scc1 .LBB0_1381
	s_waitcnt vmcnt(0)
	s_waitcnt lgkmcnt(0)
	s_barrier
	v_readlane_b32 s100, v255, 1
	v_readlane_b32 s101, v255, 2
	v_readlane_b32 s4, v254, 2
	v_readlane_b32 vcc_hi, v255, 41
	s_nop 0
	v_mov_b32_e32 v0, s4
	ds_read_b32 v0, v0
	s_nop 1
	s_load_dwordx2 s[100:101], s[100:101], 0xc0
	s_cmp_eq_u32 vcc_hi, 3
	s_cselect_b32 vcc_hi, 0, vcc_hi
	s_mul_i32 vcc_hi, vcc_hi, 0x1c00000
	s_add_u32 vcc_hi, vcc_hi, 0x100000
	s_waitcnt lgkmcnt(0)
	v_readfirstlane_b32 s4, v0
	v_and_b32_e32 v7, 1, v163
	v_lshrrev_b32_e32 v0, 1, v163
	v_lshlrev_b32_e32 v7, 7, v7
	s_and_b32 s5, s4, 7
	s_lshr_b32 s4, s4, 3
	s_lshl_b32 s5, s5, 4
	s_and_b32 vcc_lo, s4, 7
	s_add_u32 s5, s5, vcc_lo
	s_lshr_b32 s4, s4, 3
	s_mul_i32 s0, s5, 0x80000
	s_add_u32 s0, s0, 0x5500000
	s_movk_i32 s1, 0x800
	v_mad_u32_u24 v2, v0, s1, v7
	v_add_u32_e32 v2, s0, v2
	global_load_dword v2, v2, s[100:101] sc1
	s_mul_i32 s0, s4, 0x80000
	s_add_u32 s0, s0, 0x790000
	s_add_u32 s0, s0, vcc_hi
	s_movk_i32 s1, 0x800
	v_mad_u32_u24 v3, v0, s1, v7
	v_add_u32_e32 v3, s0, v3
	global_load_dword v3, v3, s[100:101] sc1
	s_and_saveexec_b64 s[0:1], s[92:93]
	v_readlane_b32 s58, v255, 17
	v_readlane_b32 s6, v255, 7
	v_readlane_b32 s52, v255, 9
	v_readlane_b32 s54, v255, 11
	v_readlane_b32 s56, v255, 13
	v_readlane_b32 s59, v255, 18
	v_readlane_b32 s7, v255, 8
	v_readlane_b32 s53, v255, 10
	v_readlane_b32 s55, v255, 12
	v_readlane_b32 s57, v255, 14
	s_cbranch_execz .LBB0_1387
	v_readlane_b32 s100, v255, 40
	v_readlane_b32 s4, v254, 6
	v_readlane_b32 s5, v254, 7
	s_mov_b32 s101, 0
	s_add_u32 s100, s100, 32
	s_nop 1
	v_writelane_b32 v255, s100, 40
	global_atomic_add v1, v218, s[4:5]
	buffer_inv sc1

; __device__ __forceinline__ void xcd_local_barrier(const XcdBarrier& b, unsigned nloc) {
;     ...
;         asm volatile("s_waitcnt vmcnt(0)" ::: "memory");
;     }
;     __syncthreads();
.LBB0_1387:
	s_or_b64 exec, exec, s[0:1]
	s_waitcnt vmcnt(0)
	s_barrier
	s_branch .LBB0_1441

; #define PG8_STAGE(bufoff, gbase, voff) do { _Pragma("unroll") for (int _i = 0; _i < 2; ++_i) \
;         __builtin_amdgcn_global_load_lds((const unsigned*)((const char*)(gbase) + (voff)[_i]), (LAS unsigned*)(lds + (bufoff) + ldsw + _i * 8192), 16, 0, 0); } while (0)
; __device__ __forceinline__ unsigned xb_ld(unsigned* p)              { return __hip_atomic_load(p, __ATOMIC_RELAXED, __HIP_MEMORY_SCOPE_AGENT); }
; __device__ __forceinline__ unsigned xb_add(unsigned* p, unsigned v) { return __hip_atomic_fetch_add(p, v, __ATOMIC_RELAXED, __HIP_MEMORY_SCOPE_AGENT); }
; #define XB_SPIN(cond, bar) do { unsigned _sp = 0; while (cond) { __builtin_amdgcn_s_sleep(1); \
;     if ((++_sp & 255u) == 0u) { if (xb_ld(&(bar)[XB_TMO])) break; if (_sp > XB_SPIN_CAP) { atomicAdd(&(bar)[XB_TMO], 1u); break; } } } } while (0)
; template <class Epi, bool MID = false>
; __device__ __forceinline__ void gemm_phase(LAS unsigned char* lds, const Gemm g, const StaticOrder& S, const Epi& E) {
;     ...
;     const char* cA = (const char*)g.A + (size_t)cur.pm * tstepA; const char* cB = (const char*)g.Bt + (size_t)cur.pn * tstepB;
;     PG8_STAGE(PG8_SB(0, 0), cB, voffB); PG8_STAGE(PG8_SB(0, 1), cB + hstepB, voffB); PG8_STAGE(PG8_SA(0, 0), cA, voffA); PG8_STAGE(PG8_SA(0, 1), cA + hstepA, voffA);
; __device__ __forceinline__ void xcd_local_barrier(const XcdBarrier& b, unsigned nloc) {
;     asm volatile("s_waitcnt vmcnt(0)" ::: "memory");
;     __syncthreads();
;     if (threadIdx.x == 0) {
;         unsigned* bar = b.bar;
;         __builtin_amdgcn_s_waitcnt(0);
;         const unsigned old = xb_add(&bar[XB_LSUB(b.x)], 1u);
;         const unsigned gen = old / nloc;
;         if (old + 1u == (gen + 1u) * nloc) xb_add(&bar[XB_LGEN(b.x)], 1u);
;         else XB_SPIN(xb_ld(&bar[XB_LGEN(b.x)]) == gen, bar);
;         __builtin_amdgcn_fence(__ATOMIC_ACQUIRE, "agent");
;         asm volatile("s_waitcnt vmcnt(0)" ::: "memory");
;     }
.LBB0_1467:
	v_readlane_b32 s0, v254, 60
	v_mov_b32 v0, s0
	ds_read_b32 v0, v0
	s_waitcnt lgkmcnt(0)
	s_nop 0
	v_readfirstlane_b32 s0, v0
	s_cmp_eq_u32 s0, 0
	s_cbranch_scc1 .LBB0_1481
	s_waitcnt vmcnt(0)
	s_waitcnt vmcnt(0) lgkmcnt(0)
	s_barrier
	v_readlane_b32 s100, v255, 1
	v_readlane_b32 s101, v255, 2
	v_readlane_b32 s4, v254, 2
	v_readlane_b32 vcc_hi, v255, 41
	s_nop 0
	v_mov_b32_e32 v0, s4
	ds_read_b32 v0, v0
	s_nop 1
	s_load_dwordx2 s[100:101], s[100:101], 0xc0
	s_cmp_eq_u32 vcc_hi, 3
	s_cselect_b32 vcc_hi, 0, vcc_hi
	s_mul_i32 vcc_hi, vcc_hi, 0x1c00000
	s_add_u32 vcc_hi, vcc_hi, 0x100000
	s_waitcnt lgkmcnt(0)
	v_readfirstlane_b32 s4, v0
	v_and_b32_e32 v7, 1, v163
	v_lshrrev_b32_e32 v0, 1, v163
	v_lshlrev_b32_e32 v7, 7, v7
	s_and_b32 s5, s4, 7
	s_lshr_b32 s4, s4, 3
	s_lshl_b32 s5, s5, 4
	s_and_b32 vcc_lo, s4, 7
	s_add_u32 s5, s5, vcc_lo
	s_lshr_b32 s4, s4, 3
	s_add_u32 s0, s5, 8
	s_mul_i32 s0, s0, 0x200000
	s_add_u32 s0, s0, 0x9500000
	s_movk_i32 s1, 0x2000
	v_mad_u32_u24 v2, v0, s1, v7
	v_add_u32_e32 v2, s0, v2
	global_load_dword v2, v2, s[100:101] sc1
	s_mul_i32 s0, s4, 0x200000
	s_add_u32 s0, s0, 0xf90000
	s_add_u32 s0, s0, vcc_hi
	s_movk_i32 s1, 0x2000
	v_mad_u32_u24 v3, v0, s1, v7
	v_add_u32_e32 v3, s0, v3
	global_load_dword v3, v3, s[100:101] sc1
	s_and_saveexec_b64 s[0:1], s[92:93]
	s_cbranch_execz .LBB0_1487
	v_readlane_b32 s100, v255, 40
	v_readlane_b32 s4, v254, 6
	v_readlane_b32 s5, v254, 7
	s_mov_b32 s101, 0
	s_add_u32 s100, s100, 32
	s_nop 1
	v_writelane_b32 v255, s100, 40
	global_atomic_add v1, v218, s[4:5]
	buffer_inv sc1

; __device__ __forceinline__ void xcd_local_barrier(const XcdBarrier& b, unsigned nloc) {
;     ...
;         asm volatile("s_waitcnt vmcnt(0)" ::: "memory");
;     }
;     __syncthreads();
.LBB0_1487:
	s_or_b64 exec, exec, s[0:1]
	v_readlane_b32 s44, v255, 9
	v_readlane_b32 s46, v255, 11
	v_readlane_b32 s52, v255, 13
	v_readlane_b32 s45, v255, 10
	v_readlane_b32 s47, v255, 12
	v_readlane_b32 s53, v255, 14
	s_waitcnt vmcnt(0)
	s_barrier
	s_branch .LBB0_1541
